# fp6 load-segment trim also on the MoE-down loop (3 address pairs precomputed)
# baseline (speedup 1.0000x reference)
.LBB0_991:
	ds_read_b128 v[146:149], v142
	ds_read_b128 v[192:195], v142 offset:1024
	ds_read_b128 v[152:155], v142 offset:2048
	ds_read_b128 v[196:199], v142 offset:3072
	ds_read_b128 v[158:161], v143
	ds_read_b128 v[200:203], v143 offset:1024
	ds_read_b128 v[164:167], v143 offset:2048
	ds_read_b128 v[204:207], v143 offset:3072
	v_lshl_add_u64 v[150:151], s[54:55], 0, v[136:137]
	s_add_i32 m0, s29, 0xc000
	ds_read_b128 v[170:173], v144
	ds_read_b128 v[208:211], v144 offset:1024
	ds_read_b128 v[176:179], v144 offset:2048
	ds_read_b128 v[212:215], v144 offset:3072
	ds_read_b128 v[182:185], v144 offset:4096
	ds_read_b128 v[216:219], v144 offset:5120
	ds_read_b128 v[188:191], v144 offset:6144
	ds_read_b128 v[220:223], v144 offset:7168
	global_load_lds_dwordx4 v[150:151], off
	s_add_i32 m0, s29, 0xe000
	v_lshl_add_u64 v[150:151], v[150:151], 0, s[10:11]
	global_load_lds_dwordx4 v[150:151], off
	s_waitcnt vmcnt(8)
	s_waitcnt lgkmcnt(0)
	s_barrier
	s_waitcnt lgkmcnt(0)
	v_mov_b32_e32 v150, v192
	v_mov_b32_e32 v151, v193
	v_mov_b32_e32 v156, v196
	v_mov_b32_e32 v157, v197
	v_mov_b32_e32 v174, v208
	v_mov_b32_e32 v175, v209
	v_mov_b32_e32 v180, v212
	v_mov_b32_e32 v181, v213
	v_mov_b32_e32 v186, v216
	v_mov_b32_e32 v187, v217
	v_mov_b32_e32 v192, v220
	v_mov_b32_e32 v193, v221
	v_mfma_scale_f32_16x16x128_f8f6f4 v[128:131], v[146:151], v[170:175], v[128:131], v194, v210 op_sel_hi:[0,0,0] cbsz:2 blgp:2
	v_mfma_scale_f32_16x16x128_f8f6f4 v[124:127], v[152:157], v[170:175], v[124:127], v198, v210 op_sel_hi:[0,0,0] cbsz:2 blgp:2
	v_mfma_scale_f32_16x16x128_f8f6f4 v[120:123], v[146:151], v[176:181], v[120:123], v194, v214 op_sel_hi:[0,0,0] cbsz:2 blgp:2
	v_mfma_scale_f32_16x16x128_f8f6f4 v[116:119], v[152:157], v[176:181], v[116:119], v198, v214 op_sel_hi:[0,0,0] cbsz:2 blgp:2
	s_add_u32 s56, s54, 0xfffc0080
	s_addc_u32 s57, s55, -1
	s_cmp_eq_u32 s86, 12
	s_cselect_b32 s57, s4, s57
	s_cselect_b32 s56, s5, s56
	s_cselect_b32 s59, s39, s85
	s_cselect_b32 s58, s45, s84
	s_add_i32 s100, s61, s24
	s_add_i32 s101, s62, s24
	v_lshl_add_u64 v[236:237], s[58:59], 0, v[132:133]
	v_lshl_add_u64 v[238:239], s[56:57], 0, v[134:135]
	v_lshl_add_u64 v[240:241], v[236:237], 0, s[10:11]
	v_lshl_add_u64 v[242:243], v[236:237], 0, s[12:13]
	v_lshl_add_u64 v[244:245], v[236:237], 0, s[14:15]
	v_lshl_add_u64 v[246:247], v[238:239], 0, s[10:11]
	v_mfma_scale_f32_16x16x128_f8f6f4 v[112:115], v[146:151], v[182:187], v[112:115], v194, v218 op_sel_hi:[0,0,0] cbsz:2 blgp:2
	v_mfma_scale_f32_16x16x128_f8f6f4 v[108:111], v[152:157], v[182:187], v[108:111], v198, v218 op_sel_hi:[0,0,0] cbsz:2 blgp:2
	v_mfma_scale_f32_16x16x128_f8f6f4 v[104:107], v[146:151], v[188:193], v[104:107], v194, v222 op_sel_hi:[0,0,0] cbsz:2 blgp:2
	v_mfma_scale_f32_16x16x128_f8f6f4 v[100:103], v[152:157], v[188:193], v[100:103], v198, v222 op_sel_hi:[0,0,0] cbsz:2 blgp:2
	v_mov_b32_e32 v168, v204
	v_mov_b32_e32 v169, v205
	v_mov_b32_e32 v162, v200
	v_mov_b32_e32 v163, v201
	v_mfma_scale_f32_16x16x128_f8f6f4 v[30:33], v[164:169], v[188:193], v[30:33], v206, v222 op_sel_hi:[0,0,0] cbsz:2 blgp:2
	s_nop 0
	v_mfma_scale_f32_16x16x128_f8f6f4 v[224:227], v[158:163], v[170:175], v[2:5], v202, v210 op_sel_hi:[0,0,0] cbsz:2 blgp:2
	v_mfma_scale_f32_16x16x128_f8f6f4 v[170:173], v[164:169], v[170:175], v[6:9], v206, v210 op_sel_hi:[0,0,0] cbsz:2 blgp:2
	v_mfma_scale_f32_16x16x128_f8f6f4 v[208:211], v[158:163], v[176:181], v[10:13], v202, v214 op_sel_hi:[0,0,0] cbsz:2 blgp:2
	v_mfma_scale_f32_16x16x128_f8f6f4 v[174:177], v[164:169], v[176:181], v[14:17], v206, v214 op_sel_hi:[0,0,0] cbsz:2 blgp:2
	v_mfma_scale_f32_16x16x128_f8f6f4 v[178:181], v[158:163], v[182:187], v[18:21], v202, v218 op_sel_hi:[0,0,0] cbsz:2 blgp:2
	v_mfma_scale_f32_16x16x128_f8f6f4 v[182:185], v[164:169], v[182:187], v[22:25], v206, v218 op_sel_hi:[0,0,0] cbsz:2 blgp:2
	v_mfma_scale_f32_16x16x128_f8f6f4 v[212:215], v[158:163], v[188:193], v[26:29], v202, v222 op_sel_hi:[0,0,0] cbsz:2 blgp:2
	s_barrier
	s_mov_b32 m0, s100
	ds_read_b128 v[2:5], v144 offset:16384
	ds_read_b128 v[24:27], v144 offset:17408
	ds_read_b128 v[8:11], v144 offset:18432
	global_load_lds_dwordx4 v[236:237], off
	s_add_i32 m0, s100, 0x2000
	ds_read_b128 v[186:189], v144 offset:19456
	global_load_lds_dwordx4 v[240:241], off
	s_mov_b32 m0, s101
	ds_read_b128 v[14:17], v144 offset:20480
	global_load_lds_dwordx4 v[242:243], off
	s_add_i32 m0, s101, 0x2000
	ds_read_b128 v[190:193], v144 offset:21504
	global_load_lds_dwordx4 v[244:245], off
	s_mov_b32 m0, s29
	ds_read_b128 v[20:23], v144 offset:22528
	global_load_lds_dwordx4 v[238:239], off
	s_mov_b32 m0, s33
	ds_read_b128 v[216:219], v144 offset:23552
	global_load_lds_dwordx4 v[246:247], off
	s_waitcnt vmcnt(8)
	s_waitcnt lgkmcnt(0)
	s_barrier
	s_waitcnt lgkmcnt(0)
	v_mov_b32_e32 v6, v24
	v_mov_b32_e32 v7, v25
	v_mov_b32_e32 v12, v186
	v_mov_b32_e32 v13, v187
	v_mov_b32_e32 v18, v190
	v_mov_b32_e32 v19, v191
	v_mfma_scale_f32_16x16x128_f8f6f4 v[96:99], v[146:151], v[2:7], v[96:99], v194, v26 op_sel_hi:[0,0,0] cbsz:2 blgp:2
	v_mov_b32_e32 v24, v216
	v_mov_b32_e32 v25, v217
	v_mfma_scale_f32_16x16x128_f8f6f4 v[92:95], v[152:157], v[2:7], v[92:95], v198, v26 op_sel_hi:[0,0,0] cbsz:2 blgp:2
	v_mfma_scale_f32_16x16x128_f8f6f4 v[80:83], v[146:151], v[8:13], v[80:83], v194, v188 op_sel_hi:[0,0,0] cbsz:2 blgp:2
	v_mfma_scale_f32_16x16x128_f8f6f4 v[76:79], v[152:157], v[8:13], v[76:79], v198, v188 op_sel_hi:[0,0,0] cbsz:2 blgp:2
	s_add_i32 s56, 0, 0x18000
	s_add_i32 s57, 0, 0x1c000
	v_add_u32_e32 v252, 0x18000, v1
	v_add_u32_e32 v253, 0x1c000, v1
	v_lshl_add_u64 v[248:249], v[238:239], 0, s[12:13]
	v_lshl_add_u64 v[250:251], v[238:239], 0, s[14:15]
	v_mfma_scale_f32_16x16x128_f8f6f4 v[68:71], v[146:151], v[14:19], v[68:71], v194, v192 op_sel_hi:[0,0,0] cbsz:2 blgp:2
	v_mfma_scale_f32_16x16x128_f8f6f4 v[56:59], v[152:157], v[14:19], v[56:59], v198, v192 op_sel_hi:[0,0,0] cbsz:2 blgp:2
	v_mfma_scale_f32_16x16x128_f8f6f4 v[194:197], v[146:151], v[20:25], v[52:55], v194, v218 op_sel_hi:[0,0,0] cbsz:2 blgp:2
	v_mfma_scale_f32_16x16x128_f8f6f4 v[198:201], v[152:157], v[20:25], v[44:47], v198, v218 op_sel_hi:[0,0,0] cbsz:2 blgp:2
	v_mfma_scale_f32_16x16x128_f8f6f4 v[88:91], v[158:163], v[2:7], v[88:91], v202, v26 op_sel_hi:[0,0,0] cbsz:2 blgp:2
	v_mfma_scale_f32_16x16x128_f8f6f4 v[84:87], v[164:169], v[2:7], v[84:87], v206, v26 op_sel_hi:[0,0,0] cbsz:2 blgp:2
	v_mfma_scale_f32_16x16x128_f8f6f4 v[72:75], v[158:163], v[8:13], v[72:75], v202, v188 op_sel_hi:[0,0,0] cbsz:2 blgp:2
	v_mfma_scale_f32_16x16x128_f8f6f4 v[186:189], v[164:169], v[8:13], v[64:67], v206, v188 op_sel_hi:[0,0,0] cbsz:2 blgp:2
	v_mfma_scale_f32_16x16x128_f8f6f4 v[220:223], v[158:163], v[14:19], v[60:63], v202, v192 op_sel_hi:[0,0,0] cbsz:2 blgp:2
	v_mfma_scale_f32_16x16x128_f8f6f4 v[190:193], v[164:169], v[14:19], v[48:51], v206, v192 op_sel_hi:[0,0,0] cbsz:2 blgp:2
	v_mfma_scale_f32_16x16x128_f8f6f4 v[202:205], v[158:163], v[20:25], v[40:43], v202, v218 op_sel_hi:[0,0,0] cbsz:2 blgp:2
	v_mfma_scale_f32_16x16x128_f8f6f4 v[216:219], v[164:169], v[20:25], v[36:39], v206, v218 op_sel_hi:[0,0,0] cbsz:2 blgp:2
	s_barrier
	s_mov_b32 m0, s40
	ds_read_b128 v[36:39], v252
	ds_read_b128 v[52:55], v252 offset:1024
	ds_read_b128 v[42:45], v252 offset:2048
	ds_read_b128 v[64:67], v252 offset:3072
	ds_read_b128 v[146:149], v253
	ds_read_b128 v[228:231], v253 offset:1024
	ds_read_b128 v[152:155], v253 offset:2048
	ds_read_b128 v[232:235], v253 offset:3072
	ds_read_b128 v[6:9], v144 offset:32768
	ds_read_b128 v[10:13], v144 offset:33792
	ds_read_b128 v[14:17], v144 offset:34816
	ds_read_b128 v[18:21], v144 offset:35840
	ds_read_b128 v[22:25], v144 offset:36864
	ds_read_b128 v[26:29], v144 offset:37888
	global_load_lds_dwordx4 v[248:249], off
	s_mov_b32 m0, s41
	ds_read_b128 v[48:51], v144 offset:38912
	ds_read_b128 v[60:63], v144 offset:39936
	global_load_lds_dwordx4 v[250:251], off
	s_waitcnt vmcnt(8)
	s_waitcnt lgkmcnt(0)
	s_barrier
	s_waitcnt lgkmcnt(0)
	v_mov_b32_e32 v40, v52
	v_mov_b32_e32 v41, v53
	v_mov_b32_e32 v46, v64
	v_mov_b32_e32 v47, v65
	v_mov_b32_e32 v52, v60
	v_mov_b32_e32 v53, v61
	v_mfma_scale_f32_16x16x128_f8f6f4 v[128:131], v[36:41], v[6:11], v[128:131], v54, v12 op_sel_hi:[0,0,0] cbsz:2 blgp:2
	v_mfma_scale_f32_16x16x128_f8f6f4 v[124:127], v[42:47], v[6:11], v[124:127], v66, v12 op_sel_hi:[0,0,0] cbsz:2 blgp:2
	v_mfma_scale_f32_16x16x128_f8f6f4 v[120:123], v[36:41], v[14:19], v[120:123], v54, v20 op_sel_hi:[0,0,0] cbsz:2 blgp:2
	v_mfma_scale_f32_16x16x128_f8f6f4 v[116:119], v[42:47], v[14:19], v[116:119], v66, v20 op_sel_hi:[0,0,0] cbsz:2 blgp:2
	s_add_i32 s100, s56, s24
	s_add_i32 s101, s57, s24
	s_add_i32 s56, s57, s24
	v_lshl_add_u64 v[240:241], v[236:237], 0, s[22:23]
	v_lshl_add_u64 v[242:243], v[236:237], 0, s[26:27]
	v_lshl_add_u64 v[244:245], v[236:237], 0, s[30:31]
	v_lshl_add_u64 v[246:247], v[236:237], 0, s[34:35]
	v_lshl_add_u64 v[248:249], v[238:239], 0, s[22:23]
	v_lshl_add_u64 v[250:251], v[238:239], 0, s[26:27]
	v_mfma_scale_f32_16x16x128_f8f6f4 v[112:115], v[36:41], v[22:27], v[112:115], v54, v28 op_sel_hi:[0,0,0] cbsz:2 blgp:2
	v_mfma_scale_f32_16x16x128_f8f6f4 v[108:111], v[42:47], v[22:27], v[108:111], v66, v28 op_sel_hi:[0,0,0] cbsz:2 blgp:2
	v_mfma_scale_f32_16x16x128_f8f6f4 v[104:107], v[36:41], v[48:53], v[104:107], v54, v62 op_sel_hi:[0,0,0] cbsz:2 blgp:2
	v_mfma_scale_f32_16x16x128_f8f6f4 v[100:103], v[42:47], v[48:53], v[100:103], v66, v62 op_sel_hi:[0,0,0] cbsz:2 blgp:2
	v_mov_b32_e32 v150, v228
	v_mov_b32_e32 v151, v229
	v_mov_b32_e32 v156, v232
	v_mov_b32_e32 v157, v233
	v_mfma_scale_f32_16x16x128_f8f6f4 v[2:5], v[146:151], v[6:11], v[224:227], v230, v12 op_sel_hi:[0,0,0] cbsz:2 blgp:2
	s_nop 0
	v_mfma_scale_f32_16x16x128_f8f6f4 v[6:9], v[152:157], v[6:11], v[170:173], v234, v12 op_sel_hi:[0,0,0] cbsz:2 blgp:2
	v_mfma_scale_f32_16x16x128_f8f6f4 v[10:13], v[146:151], v[14:19], v[208:211], v230, v20 op_sel_hi:[0,0,0] cbsz:2 blgp:2
	v_mfma_scale_f32_16x16x128_f8f6f4 v[14:17], v[152:157], v[14:19], v[174:177], v234, v20 op_sel_hi:[0,0,0] cbsz:2 blgp:2
	v_mfma_scale_f32_16x16x128_f8f6f4 v[18:21], v[146:151], v[22:27], v[178:181], v230, v28 op_sel_hi:[0,0,0] cbsz:2 blgp:2
	v_mfma_scale_f32_16x16x128_f8f6f4 v[22:25], v[152:157], v[22:27], v[182:185], v234, v28 op_sel_hi:[0,0,0] cbsz:2 blgp:2
	v_mfma_scale_f32_16x16x128_f8f6f4 v[26:29], v[146:151], v[48:53], v[212:215], v230, v62 op_sel_hi:[0,0,0] cbsz:2 blgp:2
	v_mfma_scale_f32_16x16x128_f8f6f4 v[30:33], v[152:157], v[48:53], v[30:33], v234, v62 op_sel_hi:[0,0,0] cbsz:2 blgp:2
	s_barrier
	s_mov_b32 m0, s100
	ds_read_b128 v[60:63], v144 offset:49152
	ds_read_b128 v[48:51], v144 offset:50176
	ds_read_b128 v[158:161], v144 offset:51200
	global_load_lds_dwordx4 v[240:241], off
	s_add_i32 m0, s100, 0x2000
	ds_read_b128 v[174:177], v144 offset:52224
	global_load_lds_dwordx4 v[242:243], off
	s_mov_b32 m0, s101
	ds_read_b128 v[164:167], v144 offset:53248
	global_load_lds_dwordx4 v[244:245], off
	s_add_i32 m0, s101, 0x2000
	ds_read_b128 v[178:181], v144 offset:54272
	global_load_lds_dwordx4 v[246:247], off
	s_mov_b32 m0, s43
	ds_read_b128 v[170:173], v144 offset:55296
	global_load_lds_dwordx4 v[248:249], off
	s_mov_b32 m0, s50
	ds_read_b128 v[182:185], v144 offset:56320
	global_load_lds_dwordx4 v[250:251], off
	s_waitcnt vmcnt(8)
	s_waitcnt lgkmcnt(0)
	s_barrier
	s_waitcnt lgkmcnt(0)
	v_mov_b32_e32 v64, v48
	v_mov_b32_e32 v65, v49
	v_mov_b32_e32 v162, v174
	v_mov_b32_e32 v163, v175
	v_mov_b32_e32 v168, v178
	v_mov_b32_e32 v169, v179
	v_mov_b32_e32 v174, v182
	v_mov_b32_e32 v175, v183
	v_mfma_scale_f32_16x16x128_f8f6f4 v[96:99], v[36:41], v[60:65], v[96:99], v54, v50 op_sel_hi:[0,0,0] cbsz:2 blgp:2
	v_mfma_scale_f32_16x16x128_f8f6f4 v[92:95], v[42:47], v[60:65], v[92:95], v66, v50 op_sel_hi:[0,0,0] cbsz:2 blgp:2
	v_mfma_scale_f32_16x16x128_f8f6f4 v[80:83], v[36:41], v[158:163], v[80:83], v54, v176 op_sel_hi:[0,0,0] cbsz:2 blgp:2
	v_mfma_scale_f32_16x16x128_f8f6f4 v[76:79], v[42:47], v[158:163], v[76:79], v66, v176 op_sel_hi:[0,0,0] cbsz:2 blgp:2
	v_mfma_scale_f32_16x16x128_f8f6f4 v[68:71], v[36:41], v[164:169], v[68:71], v54, v180 op_sel_hi:[0,0,0] cbsz:2 blgp:2
	v_mfma_scale_f32_16x16x128_f8f6f4 v[56:59], v[42:47], v[164:169], v[56:59], v66, v180 op_sel_hi:[0,0,0] cbsz:2 blgp:2
	v_mfma_scale_f32_16x16x128_f8f6f4 v[52:55], v[36:41], v[170:175], v[194:197], v54, v184 op_sel_hi:[0,0,0] cbsz:2 blgp:2
	v_mfma_scale_f32_16x16x128_f8f6f4 v[44:47], v[42:47], v[170:175], v[198:201], v66, v184 op_sel_hi:[0,0,0] cbsz:2 blgp:2
	v_mfma_scale_f32_16x16x128_f8f6f4 v[88:91], v[146:151], v[60:65], v[88:91], v230, v50 op_sel_hi:[0,0,0] cbsz:2 blgp:2
	v_mfma_scale_f32_16x16x128_f8f6f4 v[84:87], v[152:157], v[60:65], v[84:87], v234, v50 op_sel_hi:[0,0,0] cbsz:2 blgp:2
	v_mfma_scale_f32_16x16x128_f8f6f4 v[72:75], v[146:151], v[158:163], v[72:75], v230, v176 op_sel_hi:[0,0,0] cbsz:2 blgp:2
	v_mfma_scale_f32_16x16x128_f8f6f4 v[64:67], v[152:157], v[158:163], v[186:189], v234, v176 op_sel_hi:[0,0,0] cbsz:2 blgp:2
	v_mfma_scale_f32_16x16x128_f8f6f4 v[60:63], v[146:151], v[164:169], v[220:223], v230, v180 op_sel_hi:[0,0,0] cbsz:2 blgp:2
	v_mfma_scale_f32_16x16x128_f8f6f4 v[48:51], v[152:157], v[164:169], v[190:193], v234, v180 op_sel_hi:[0,0,0] cbsz:2 blgp:2
	v_mfma_scale_f32_16x16x128_f8f6f4 v[40:43], v[146:151], v[170:175], v[202:205], v230, v184 op_sel_hi:[0,0,0] cbsz:2 blgp:2
	v_mfma_scale_f32_16x16x128_f8f6f4 v[36:39], v[152:157], v[170:175], v[216:219], v234, v184 op_sel_hi:[0,0,0] cbsz:2 blgp:2
	s_barrier
	s_add_i32 s86, s86, 2
	s_add_u32 s54, s54, 0x100
	s_addc_u32 s55, s55, 0
	s_add_u32 s84, s84, 0x100
	s_addc_u32 s85, s85, 0
	s_cmp_gt_u32 s86, 13
	s_cbranch_scc0 .LBB0_991
	s_setprio 0
	s_and_b64 vcc, exec, s[36:37]
	s_cbranch_vccz .LBB0_994
	s_barrier

.LBB0_2187:
	ds_read_b128 v[142:145], v138
	ds_read_b128 v[188:191], v138 offset:1024
	ds_read_b128 v[148:151], v138 offset:2048
	ds_read_b128 v[192:195], v138 offset:3072
	ds_read_b128 v[154:157], v139
	ds_read_b128 v[196:199], v139 offset:1024
	ds_read_b128 v[160:163], v139 offset:2048
	ds_read_b128 v[200:203], v139 offset:3072
	v_lshl_add_u64 v[146:147], s[48:49], 0, v[136:137]
	s_add_i32 m0, s33, 0xc000
	ds_read_b128 v[166:169], v140
	ds_read_b128 v[204:207], v140 offset:1024
	ds_read_b128 v[172:175], v140 offset:2048
	ds_read_b128 v[208:211], v140 offset:3072
	ds_read_b128 v[178:181], v140 offset:4096
	ds_read_b128 v[212:215], v140 offset:5120
	ds_read_b128 v[184:187], v140 offset:6144
	ds_read_b128 v[216:219], v140 offset:7168
	global_load_lds_dwordx4 v[146:147], off
	s_add_i32 m0, s33, 0xe000
	v_lshl_add_u64 v[146:147], v[146:147], 0, s[6:7]
	global_load_lds_dwordx4 v[146:147], off
	s_waitcnt vmcnt(8)
	s_waitcnt lgkmcnt(0)
	s_barrier
	s_waitcnt lgkmcnt(0)
	v_mov_b32_e32 v146, v188
	v_mov_b32_e32 v147, v189
	v_mov_b32_e32 v152, v192
	v_mov_b32_e32 v153, v193
	v_mov_b32_e32 v170, v204
	v_mov_b32_e32 v171, v205
	v_mov_b32_e32 v176, v208
	v_mov_b32_e32 v177, v209
	v_mov_b32_e32 v182, v212
	v_mov_b32_e32 v183, v213
	v_mov_b32_e32 v188, v216
	v_mov_b32_e32 v189, v217
	v_mfma_scale_f32_16x16x128_f8f6f4 v[128:131], v[142:147], v[166:171], v[128:131], v190, v206 op_sel_hi:[0,0,0] cbsz:2 blgp:2
	v_mfma_scale_f32_16x16x128_f8f6f4 v[124:127], v[148:153], v[166:171], v[124:127], v194, v206 op_sel_hi:[0,0,0] cbsz:2 blgp:2
	v_mfma_scale_f32_16x16x128_f8f6f4 v[120:123], v[142:147], v[172:177], v[120:123], v190, v210 op_sel_hi:[0,0,0] cbsz:2 blgp:2
	v_mfma_scale_f32_16x16x128_f8f6f4 v[116:119], v[148:153], v[172:177], v[116:119], v194, v210 op_sel_hi:[0,0,0] cbsz:2 blgp:2
	s_add_u32 s50, s48, 0xfffc0080
	s_addc_u32 s51, s49, -1
	s_cmp_eq_u32 s76, 12
	s_cselect_b32 s51, s35, s51
	s_cselect_b32 s50, s47, s50
	s_cselect_b32 s53, s37, s67
	s_cselect_b32 s52, s65, s66
	s_add_i32 s100, s57, s29
	s_add_i32 s101, s58, s29
	v_lshl_add_u64 v[232:233], s[52:53], 0, v[132:133]
	v_lshl_add_u64 v[234:235], s[50:51], 0, v[134:135]
	v_lshl_add_u64 v[240:241], v[232:233], 0, s[6:7]
	v_lshl_add_u64 v[242:243], v[232:233], 0, s[8:9]
	v_lshl_add_u64 v[244:245], v[232:233], 0, s[10:11]
	v_lshl_add_u64 v[246:247], v[234:235], 0, s[6:7]
	v_mfma_scale_f32_16x16x128_f8f6f4 v[112:115], v[142:147], v[178:183], v[112:115], v190, v214 op_sel_hi:[0,0,0] cbsz:2 blgp:2
	v_mfma_scale_f32_16x16x128_f8f6f4 v[108:111], v[148:153], v[178:183], v[108:111], v194, v214 op_sel_hi:[0,0,0] cbsz:2 blgp:2
	v_mfma_scale_f32_16x16x128_f8f6f4 v[104:107], v[142:147], v[184:189], v[104:107], v190, v218 op_sel_hi:[0,0,0] cbsz:2 blgp:2
	v_mfma_scale_f32_16x16x128_f8f6f4 v[100:103], v[148:153], v[184:189], v[100:103], v194, v218 op_sel_hi:[0,0,0] cbsz:2 blgp:2
	v_mov_b32_e32 v164, v200
	v_mov_b32_e32 v165, v201
	v_mov_b32_e32 v158, v196
	v_mov_b32_e32 v159, v197
	v_mfma_scale_f32_16x16x128_f8f6f4 v[30:33], v[160:165], v[184:189], v[30:33], v202, v218 op_sel_hi:[0,0,0] cbsz:2 blgp:2
	s_nop 0
	v_mfma_scale_f32_16x16x128_f8f6f4 v[220:223], v[154:159], v[166:171], v[2:5], v198, v206 op_sel_hi:[0,0,0] cbsz:2 blgp:2
	v_mfma_scale_f32_16x16x128_f8f6f4 v[166:169], v[160:165], v[166:171], v[6:9], v202, v206 op_sel_hi:[0,0,0] cbsz:2 blgp:2
	v_mfma_scale_f32_16x16x128_f8f6f4 v[204:207], v[154:159], v[172:177], v[10:13], v198, v210 op_sel_hi:[0,0,0] cbsz:2 blgp:2
	v_mfma_scale_f32_16x16x128_f8f6f4 v[170:173], v[160:165], v[172:177], v[14:17], v202, v210 op_sel_hi:[0,0,0] cbsz:2 blgp:2
	v_mfma_scale_f32_16x16x128_f8f6f4 v[174:177], v[154:159], v[178:183], v[18:21], v198, v214 op_sel_hi:[0,0,0] cbsz:2 blgp:2
	v_mfma_scale_f32_16x16x128_f8f6f4 v[178:181], v[160:165], v[178:183], v[22:25], v202, v214 op_sel_hi:[0,0,0] cbsz:2 blgp:2
	v_mfma_scale_f32_16x16x128_f8f6f4 v[208:211], v[154:159], v[184:189], v[26:29], v198, v218 op_sel_hi:[0,0,0] cbsz:2 blgp:2
	s_barrier
	s_mov_b32 m0, s100
	ds_read_b128 v[2:5], v140 offset:16384
	ds_read_b128 v[24:27], v140 offset:17408
	ds_read_b128 v[8:11], v140 offset:18432
	global_load_lds_dwordx4 v[232:233], off
	s_add_i32 m0, s100, 0x2000
	ds_read_b128 v[182:185], v140 offset:19456
	global_load_lds_dwordx4 v[240:241], off
	s_mov_b32 m0, s101
	ds_read_b128 v[14:17], v140 offset:20480
	global_load_lds_dwordx4 v[242:243], off
	s_add_i32 m0, s101, 0x2000
	ds_read_b128 v[186:189], v140 offset:21504
	global_load_lds_dwordx4 v[244:245], off
	s_mov_b32 m0, s33
	ds_read_b128 v[20:23], v140 offset:22528
	global_load_lds_dwordx4 v[234:235], off
	s_mov_b32 m0, s40
	ds_read_b128 v[212:215], v140 offset:23552
	global_load_lds_dwordx4 v[246:247], off
	s_waitcnt vmcnt(8)
	s_waitcnt lgkmcnt(0)
	s_barrier
	s_waitcnt lgkmcnt(0)
	v_mov_b32_e32 v6, v24
	v_mov_b32_e32 v7, v25
	v_mov_b32_e32 v12, v182
	v_mov_b32_e32 v13, v183
	v_mov_b32_e32 v18, v186
	v_mov_b32_e32 v19, v187
	v_mfma_scale_f32_16x16x128_f8f6f4 v[96:99], v[142:147], v[2:7], v[96:99], v190, v26 op_sel_hi:[0,0,0] cbsz:2 blgp:2
	v_mov_b32_e32 v24, v212
	v_mov_b32_e32 v25, v213
	v_mfma_scale_f32_16x16x128_f8f6f4 v[92:95], v[148:153], v[2:7], v[92:95], v194, v26 op_sel_hi:[0,0,0] cbsz:2 blgp:2
	v_mfma_scale_f32_16x16x128_f8f6f4 v[80:83], v[142:147], v[8:13], v[80:83], v190, v184 op_sel_hi:[0,0,0] cbsz:2 blgp:2
	v_mfma_scale_f32_16x16x128_f8f6f4 v[76:79], v[148:153], v[8:13], v[76:79], v194, v184 op_sel_hi:[0,0,0] cbsz:2 blgp:2
	s_add_i32 s50, 0, 0x18000
	s_add_i32 s51, 0, 0x1c000
	v_add_u32_e32 v252, 0x18000, v1
	v_add_u32_e32 v253, 0x1c000, v1
	v_lshl_add_u64 v[248:249], v[234:235], 0, s[8:9]
	v_lshl_add_u64 v[250:251], v[234:235], 0, s[10:11]
	v_mfma_scale_f32_16x16x128_f8f6f4 v[68:71], v[142:147], v[14:19], v[68:71], v190, v188 op_sel_hi:[0,0,0] cbsz:2 blgp:2
	v_mfma_scale_f32_16x16x128_f8f6f4 v[56:59], v[148:153], v[14:19], v[56:59], v194, v188 op_sel_hi:[0,0,0] cbsz:2 blgp:2
	v_mfma_scale_f32_16x16x128_f8f6f4 v[190:193], v[142:147], v[20:25], v[52:55], v190, v214 op_sel_hi:[0,0,0] cbsz:2 blgp:2
	v_mfma_scale_f32_16x16x128_f8f6f4 v[194:197], v[148:153], v[20:25], v[44:47], v194, v214 op_sel_hi:[0,0,0] cbsz:2 blgp:2
	v_mfma_scale_f32_16x16x128_f8f6f4 v[88:91], v[154:159], v[2:7], v[88:91], v198, v26 op_sel_hi:[0,0,0] cbsz:2 blgp:2
	v_mfma_scale_f32_16x16x128_f8f6f4 v[84:87], v[160:165], v[2:7], v[84:87], v202, v26 op_sel_hi:[0,0,0] cbsz:2 blgp:2
	v_mfma_scale_f32_16x16x128_f8f6f4 v[72:75], v[154:159], v[8:13], v[72:75], v198, v184 op_sel_hi:[0,0,0] cbsz:2 blgp:2
	v_mfma_scale_f32_16x16x128_f8f6f4 v[182:185], v[160:165], v[8:13], v[64:67], v202, v184 op_sel_hi:[0,0,0] cbsz:2 blgp:2
	v_mfma_scale_f32_16x16x128_f8f6f4 v[216:219], v[154:159], v[14:19], v[60:63], v198, v188 op_sel_hi:[0,0,0] cbsz:2 blgp:2
	v_mfma_scale_f32_16x16x128_f8f6f4 v[186:189], v[160:165], v[14:19], v[48:51], v202, v188 op_sel_hi:[0,0,0] cbsz:2 blgp:2
	v_mfma_scale_f32_16x16x128_f8f6f4 v[198:201], v[154:159], v[20:25], v[40:43], v198, v214 op_sel_hi:[0,0,0] cbsz:2 blgp:2
	v_mfma_scale_f32_16x16x128_f8f6f4 v[212:215], v[160:165], v[20:25], v[36:39], v202, v214 op_sel_hi:[0,0,0] cbsz:2 blgp:2
	s_barrier
	s_mov_b32 m0, s41
	ds_read_b128 v[36:39], v252
	ds_read_b128 v[52:55], v252 offset:1024
	ds_read_b128 v[42:45], v252 offset:2048
	ds_read_b128 v[64:67], v252 offset:3072
	ds_read_b128 v[142:145], v253
	ds_read_b128 v[224:227], v253 offset:1024
	ds_read_b128 v[148:151], v253 offset:2048
	ds_read_b128 v[228:231], v253 offset:3072
	ds_read_b128 v[6:9], v140 offset:32768
	ds_read_b128 v[10:13], v140 offset:33792
	ds_read_b128 v[14:17], v140 offset:34816
	ds_read_b128 v[18:21], v140 offset:35840
	ds_read_b128 v[22:25], v140 offset:36864
	ds_read_b128 v[26:29], v140 offset:37888
	global_load_lds_dwordx4 v[248:249], off
	s_mov_b32 m0, s42
	ds_read_b128 v[48:51], v140 offset:38912
	ds_read_b128 v[60:63], v140 offset:39936
	global_load_lds_dwordx4 v[250:251], off
	s_waitcnt vmcnt(8)
	s_waitcnt lgkmcnt(0)
	s_barrier
	s_waitcnt lgkmcnt(0)
	v_mov_b32_e32 v40, v52
	v_mov_b32_e32 v41, v53
	v_mov_b32_e32 v46, v64
	v_mov_b32_e32 v47, v65
	v_mov_b32_e32 v52, v60
	v_mov_b32_e32 v53, v61
	v_mfma_scale_f32_16x16x128_f8f6f4 v[128:131], v[36:41], v[6:11], v[128:131], v54, v12 op_sel_hi:[0,0,0] cbsz:2 blgp:2
	v_mfma_scale_f32_16x16x128_f8f6f4 v[124:127], v[42:47], v[6:11], v[124:127], v66, v12 op_sel_hi:[0,0,0] cbsz:2 blgp:2
	v_mfma_scale_f32_16x16x128_f8f6f4 v[120:123], v[36:41], v[14:19], v[120:123], v54, v20 op_sel_hi:[0,0,0] cbsz:2 blgp:2
	v_mfma_scale_f32_16x16x128_f8f6f4 v[116:119], v[42:47], v[14:19], v[116:119], v66, v20 op_sel_hi:[0,0,0] cbsz:2 blgp:2
	s_add_i32 s100, s50, s29
	s_add_i32 s101, s51, s29
	s_add_i32 s50, s51, s29
	v_lshl_add_u64 v[240:241], v[232:233], 0, s[20:21]
	v_lshl_add_u64 v[242:243], v[232:233], 0, s[22:23]
	v_lshl_add_u64 v[244:245], v[232:233], 0, s[24:25]
	v_lshl_add_u64 v[246:247], v[232:233], 0, s[26:27]
	v_lshl_add_u64 v[248:249], v[234:235], 0, s[20:21]
	v_lshl_add_u64 v[250:251], v[234:235], 0, s[22:23]
	v_mfma_scale_f32_16x16x128_f8f6f4 v[112:115], v[36:41], v[22:27], v[112:115], v54, v28 op_sel_hi:[0,0,0] cbsz:2 blgp:2
	v_mfma_scale_f32_16x16x128_f8f6f4 v[108:111], v[42:47], v[22:27], v[108:111], v66, v28 op_sel_hi:[0,0,0] cbsz:2 blgp:2
	v_mfma_scale_f32_16x16x128_f8f6f4 v[104:107], v[36:41], v[48:53], v[104:107], v54, v62 op_sel_hi:[0,0,0] cbsz:2 blgp:2
	v_mfma_scale_f32_16x16x128_f8f6f4 v[100:103], v[42:47], v[48:53], v[100:103], v66, v62 op_sel_hi:[0,0,0] cbsz:2 blgp:2
	v_mov_b32_e32 v146, v224
	v_mov_b32_e32 v147, v225
	v_mov_b32_e32 v152, v228
	v_mov_b32_e32 v153, v229
	v_mfma_scale_f32_16x16x128_f8f6f4 v[2:5], v[142:147], v[6:11], v[220:223], v226, v12 op_sel_hi:[0,0,0] cbsz:2 blgp:2
	s_nop 0
	v_mfma_scale_f32_16x16x128_f8f6f4 v[6:9], v[148:153], v[6:11], v[166:169], v230, v12 op_sel_hi:[0,0,0] cbsz:2 blgp:2
	v_mfma_scale_f32_16x16x128_f8f6f4 v[10:13], v[142:147], v[14:19], v[204:207], v226, v20 op_sel_hi:[0,0,0] cbsz:2 blgp:2
	v_mfma_scale_f32_16x16x128_f8f6f4 v[14:17], v[148:153], v[14:19], v[170:173], v230, v20 op_sel_hi:[0,0,0] cbsz:2 blgp:2
	v_mfma_scale_f32_16x16x128_f8f6f4 v[18:21], v[142:147], v[22:27], v[174:177], v226, v28 op_sel_hi:[0,0,0] cbsz:2 blgp:2
	v_mfma_scale_f32_16x16x128_f8f6f4 v[22:25], v[148:153], v[22:27], v[178:181], v230, v28 op_sel_hi:[0,0,0] cbsz:2 blgp:2
	v_mfma_scale_f32_16x16x128_f8f6f4 v[26:29], v[142:147], v[48:53], v[208:211], v226, v62 op_sel_hi:[0,0,0] cbsz:2 blgp:2
	v_mfma_scale_f32_16x16x128_f8f6f4 v[30:33], v[148:153], v[48:53], v[30:33], v230, v62 op_sel_hi:[0,0,0] cbsz:2 blgp:2
	s_barrier
	s_mov_b32 m0, s100
	ds_read_b128 v[60:63], v140 offset:49152
	ds_read_b128 v[48:51], v140 offset:50176
	ds_read_b128 v[154:157], v140 offset:51200
	global_load_lds_dwordx4 v[240:241], off
	s_add_i32 m0, s100, 0x2000
	ds_read_b128 v[170:173], v140 offset:52224
	global_load_lds_dwordx4 v[242:243], off
	s_mov_b32 m0, s101
	ds_read_b128 v[160:163], v140 offset:53248
	global_load_lds_dwordx4 v[244:245], off
	s_add_i32 m0, s101, 0x2000
	ds_read_b128 v[174:177], v140 offset:54272
	global_load_lds_dwordx4 v[246:247], off
	s_mov_b32 m0, s43
	ds_read_b128 v[166:169], v140 offset:55296
	global_load_lds_dwordx4 v[248:249], off
	s_mov_b32 m0, s54
	ds_read_b128 v[178:181], v140 offset:56320
	global_load_lds_dwordx4 v[250:251], off
	s_waitcnt vmcnt(8)
	s_waitcnt lgkmcnt(0)
	s_barrier
	s_waitcnt lgkmcnt(0)
	v_mov_b32_e32 v64, v48
	v_mov_b32_e32 v65, v49
	v_mov_b32_e32 v158, v170
	v_mov_b32_e32 v159, v171
	v_mov_b32_e32 v164, v174
	v_mov_b32_e32 v165, v175
	v_mov_b32_e32 v170, v178
	v_mov_b32_e32 v171, v179
	v_mfma_scale_f32_16x16x128_f8f6f4 v[96:99], v[36:41], v[60:65], v[96:99], v54, v50 op_sel_hi:[0,0,0] cbsz:2 blgp:2
	v_mfma_scale_f32_16x16x128_f8f6f4 v[92:95], v[42:47], v[60:65], v[92:95], v66, v50 op_sel_hi:[0,0,0] cbsz:2 blgp:2
	v_mfma_scale_f32_16x16x128_f8f6f4 v[80:83], v[36:41], v[154:159], v[80:83], v54, v172 op_sel_hi:[0,0,0] cbsz:2 blgp:2
	v_mfma_scale_f32_16x16x128_f8f6f4 v[76:79], v[42:47], v[154:159], v[76:79], v66, v172 op_sel_hi:[0,0,0] cbsz:2 blgp:2
	v_mfma_scale_f32_16x16x128_f8f6f4 v[68:71], v[36:41], v[160:165], v[68:71], v54, v176 op_sel_hi:[0,0,0] cbsz:2 blgp:2
	v_mfma_scale_f32_16x16x128_f8f6f4 v[56:59], v[42:47], v[160:165], v[56:59], v66, v176 op_sel_hi:[0,0,0] cbsz:2 blgp:2
	v_mfma_scale_f32_16x16x128_f8f6f4 v[52:55], v[36:41], v[166:171], v[190:193], v54, v180 op_sel_hi:[0,0,0] cbsz:2 blgp:2
	v_mfma_scale_f32_16x16x128_f8f6f4 v[44:47], v[42:47], v[166:171], v[194:197], v66, v180 op_sel_hi:[0,0,0] cbsz:2 blgp:2
	v_mfma_scale_f32_16x16x128_f8f6f4 v[88:91], v[142:147], v[60:65], v[88:91], v226, v50 op_sel_hi:[0,0,0] cbsz:2 blgp:2
	v_mfma_scale_f32_16x16x128_f8f6f4 v[84:87], v[148:153], v[60:65], v[84:87], v230, v50 op_sel_hi:[0,0,0] cbsz:2 blgp:2
	v_mfma_scale_f32_16x16x128_f8f6f4 v[72:75], v[142:147], v[154:159], v[72:75], v226, v172 op_sel_hi:[0,0,0] cbsz:2 blgp:2
	v_mfma_scale_f32_16x16x128_f8f6f4 v[64:67], v[148:153], v[154:159], v[182:185], v230, v172 op_sel_hi:[0,0,0] cbsz:2 blgp:2
	v_mfma_scale_f32_16x16x128_f8f6f4 v[60:63], v[142:147], v[160:165], v[216:219], v226, v176 op_sel_hi:[0,0,0] cbsz:2 blgp:2
	v_mfma_scale_f32_16x16x128_f8f6f4 v[48:51], v[148:153], v[160:165], v[186:189], v230, v176 op_sel_hi:[0,0,0] cbsz:2 blgp:2
	v_mfma_scale_f32_16x16x128_f8f6f4 v[40:43], v[142:147], v[166:171], v[198:201], v226, v180 op_sel_hi:[0,0,0] cbsz:2 blgp:2
	v_mfma_scale_f32_16x16x128_f8f6f4 v[36:39], v[148:153], v[166:171], v[212:215], v230, v180 op_sel_hi:[0,0,0] cbsz:2 blgp:2
	s_barrier
	s_add_i32 s76, s76, 2
	s_add_u32 s48, s48, 0x100
	s_addc_u32 s49, s49, 0
	s_add_u32 s66, s66, 0x100
	s_addc_u32 s67, s67, 0
	s_cmp_gt_u32 s76, 13
	s_cbranch_scc0 .LBB0_2187
	s_setprio 0
	s_and_b64 vcc, exec, s[30:31]
	s_cbranch_vccz .LBB0_2190
	s_barrier

.LBB0_2291:
	ds_read_b128 v[144:147], v140
	ds_read_b128 v[190:193], v140 offset:1024
	ds_read_b128 v[150:153], v140 offset:2048
	ds_read_b128 v[194:197], v140 offset:3072
	ds_read_b128 v[156:159], v141
	ds_read_b128 v[198:201], v141 offset:1024
	ds_read_b128 v[162:165], v141 offset:2048
	ds_read_b128 v[202:205], v141 offset:3072
	v_lshl_add_u64 v[138:139], s[44:45], 0, v[136:137]
	s_add_i32 m0, s33, 0xc000
	ds_read_b128 v[168:171], v142
	ds_read_b128 v[206:209], v142 offset:1024
	ds_read_b128 v[174:177], v142 offset:2048
	ds_read_b128 v[210:213], v142 offset:3072
	ds_read_b128 v[180:183], v142 offset:4096
	ds_read_b128 v[214:217], v142 offset:5120
	ds_read_b128 v[186:189], v142 offset:6144
	ds_read_b128 v[218:221], v142 offset:7168
	global_load_lds_dwordx4 v[138:139], off
	s_add_i32 m0, s33, 0xe000
	v_lshl_add_u64 v[138:139], v[138:139], 0, s[8:9]
	global_load_lds_dwordx4 v[138:139], off
	s_waitcnt vmcnt(8)
	s_waitcnt lgkmcnt(0)
	s_barrier
	s_waitcnt lgkmcnt(0)
	v_mov_b32_e32 v148, v190
	v_mov_b32_e32 v149, v191
	v_mov_b32_e32 v154, v194
	v_mov_b32_e32 v155, v195
	v_mov_b32_e32 v172, v206
	v_mov_b32_e32 v173, v207
	v_mov_b32_e32 v178, v210
	v_mov_b32_e32 v179, v211
	v_mov_b32_e32 v184, v214
	v_mov_b32_e32 v185, v215
	v_mfma_scale_f32_16x16x128_f8f6f4 v[126:129], v[144:149], v[168:173], v[126:129], v192, v208 op_sel_hi:[0,0,0] cbsz:2 blgp:2
	v_mov_b32_e32 v190, v218
	v_mov_b32_e32 v191, v219
	v_mfma_scale_f32_16x16x128_f8f6f4 v[122:125], v[150:155], v[168:173], v[122:125], v196, v208 op_sel_hi:[0,0,0] cbsz:2 blgp:2
	v_mfma_scale_f32_16x16x128_f8f6f4 v[110:113], v[144:149], v[174:179], v[110:113], v192, v212 op_sel_hi:[0,0,0] cbsz:2 blgp:2
	v_mfma_scale_f32_16x16x128_f8f6f4 v[106:109], v[150:155], v[174:179], v[106:109], v196, v212 op_sel_hi:[0,0,0] cbsz:2 blgp:2
	s_add_i32 s76, s46, 2
	s_add_u32 s48, s44, 0xfff20080
	s_addc_u32 s47, s45, -1
	s_cmp_eq_u32 s4, s46
	s_cselect_b32 s46, s38, s48
	s_cselect_b32 s47, s39, s47
	s_cselect_b32 s49, s7, s67
	s_cselect_b32 s48, s6, s5
	s_add_i32 s100, s58, s29
	s_add_i32 s101, s59, s29
	v_lshl_add_u64 v[138:139], s[48:49], 0, v[132:133]
	v_lshl_add_u64 v[246:247], s[46:47], 0, v[130:131]
	v_lshl_add_u64 v[248:249], v[138:139], 0, s[8:9]
	v_lshl_add_u64 v[250:251], v[138:139], 0, s[10:11]
	v_lshl_add_u64 v[252:253], v[138:139], 0, s[12:13]
	v_mfma_scale_f32_16x16x128_f8f6f4 v[94:97], v[144:149], v[180:185], v[94:97], v192, v216 op_sel_hi:[0,0,0] cbsz:2 blgp:2
	v_mfma_scale_f32_16x16x128_f8f6f4 v[90:93], v[150:155], v[180:185], v[90:93], v196, v216 op_sel_hi:[0,0,0] cbsz:2 blgp:2
	v_mfma_scale_f32_16x16x128_f8f6f4 v[222:225], v[144:149], v[186:191], v[78:81], v192, v220 op_sel_hi:[0,0,0] cbsz:2 blgp:2
	v_mfma_scale_f32_16x16x128_f8f6f4 v[226:229], v[150:155], v[186:191], v[74:77], v196, v220 op_sel_hi:[0,0,0] cbsz:2 blgp:2
	v_mov_b32_e32 v160, v198
	v_mov_b32_e32 v161, v199
	v_mov_b32_e32 v166, v202
	v_mov_b32_e32 v167, v203
	v_mfma_scale_f32_16x16x128_f8f6f4 v[118:121], v[156:161], v[168:173], v[118:121], v200, v208 op_sel_hi:[0,0,0] cbsz:2 blgp:2
	s_nop 0
	v_mfma_scale_f32_16x16x128_f8f6f4 v[114:117], v[162:167], v[168:173], v[114:117], v204, v208 op_sel_hi:[0,0,0] cbsz:2 blgp:2
	v_mfma_scale_f32_16x16x128_f8f6f4 v[102:105], v[156:161], v[174:179], v[102:105], v200, v212 op_sel_hi:[0,0,0] cbsz:2 blgp:2
	v_mfma_scale_f32_16x16x128_f8f6f4 v[98:101], v[162:167], v[174:179], v[98:101], v204, v212 op_sel_hi:[0,0,0] cbsz:2 blgp:2
	v_mfma_scale_f32_16x16x128_f8f6f4 v[168:171], v[156:161], v[180:185], v[86:89], v200, v216 op_sel_hi:[0,0,0] cbsz:2 blgp:2
	v_mfma_scale_f32_16x16x128_f8f6f4 v[172:175], v[162:167], v[180:185], v[82:85], v204, v216 op_sel_hi:[0,0,0] cbsz:2 blgp:2
	v_mfma_scale_f32_16x16x128_f8f6f4 v[176:179], v[156:161], v[186:191], v[70:73], v200, v220 op_sel_hi:[0,0,0] cbsz:2 blgp:2
	v_mfma_scale_f32_16x16x128_f8f6f4 v[180:183], v[162:167], v[186:191], v[66:69], v204, v220 op_sel_hi:[0,0,0] cbsz:2 blgp:2
	s_barrier
	s_mov_b32 m0, s100
	ds_read_b128 v[66:69], v142 offset:16384
	ds_read_b128 v[184:187], v142 offset:17408
	ds_read_b128 v[72:75], v142 offset:18432
	global_load_lds_dwordx4 v[138:139], off
	s_add_i32 m0, s100, 0x2000
	ds_read_b128 v[188:191], v142 offset:19456
	global_load_lds_dwordx4 v[248:249], off
	s_mov_b32 m0, s101
	ds_read_b128 v[78:81], v142 offset:20480
	global_load_lds_dwordx4 v[250:251], off
	s_add_i32 m0, s101, 0x2000
	ds_read_b128 v[206:209], v142 offset:21504
	global_load_lds_dwordx4 v[252:253], off
	s_mov_b32 m0, s33
	ds_read_b128 v[84:87], v142 offset:22528
	global_load_lds_dwordx4 v[246:247], off
	s_mov_b32 m0, s40
	v_lshl_add_u64 v[70:71], v[246:247], 0, s[8:9]
	ds_read_b128 v[210:213], v142 offset:23552
	global_load_lds_dwordx4 v[70:71], off
	s_waitcnt vmcnt(8)
	s_waitcnt lgkmcnt(0)
	s_barrier
	s_waitcnt lgkmcnt(0)
	v_mov_b32_e32 v70, v184
	v_mov_b32_e32 v71, v185
	v_mov_b32_e32 v76, v188
	v_mov_b32_e32 v77, v189
	v_mfma_scale_f32_16x16x128_f8f6f4 v[62:65], v[144:149], v[66:71], v[62:65], v192, v186 op_sel_hi:[0,0,0] cbsz:2 blgp:2
	v_mov_b32_e32 v82, v206
	v_mov_b32_e32 v83, v207
	v_mov_b32_e32 v88, v210
	v_mfma_scale_f32_16x16x128_f8f6f4 v[58:61], v[150:155], v[66:71], v[58:61], v196, v186 op_sel_hi:[0,0,0] cbsz:2 blgp:2
	v_mov_b32_e32 v89, v211
	v_mfma_scale_f32_16x16x128_f8f6f4 v[46:49], v[144:149], v[72:77], v[46:49], v192, v190 op_sel_hi:[0,0,0] cbsz:2 blgp:2
	v_mfma_scale_f32_16x16x128_f8f6f4 v[42:45], v[150:155], v[72:77], v[42:45], v196, v190 op_sel_hi:[0,0,0] cbsz:2 blgp:2
	s_add_i32 s46, 0, 0x18000
	s_add_i32 s47, 0, 0x1c000
	v_add_u32_e32 v143, 0x18000, v1
	v_add_u32_e32 v134, 0x1c000, v1
	v_lshl_add_u64 v[248:249], v[246:247], 0, s[10:11]
	v_lshl_add_u64 v[250:251], v[246:247], 0, s[12:13]
	v_mfma_scale_f32_16x16x128_f8f6f4 v[214:217], v[144:149], v[78:83], v[30:33], v192, v208 op_sel_hi:[0,0,0] cbsz:2 blgp:2
	v_mfma_scale_f32_16x16x128_f8f6f4 v[218:221], v[150:155], v[78:83], v[26:29], v196, v208 op_sel_hi:[0,0,0] cbsz:2 blgp:2
	v_mfma_scale_f32_16x16x128_f8f6f4 v[192:195], v[144:149], v[84:89], v[14:17], v192, v212 op_sel_hi:[0,0,0] cbsz:2 blgp:2
	v_mfma_scale_f32_16x16x128_f8f6f4 v[196:199], v[150:155], v[84:89], v[10:13], v196, v212 op_sel_hi:[0,0,0] cbsz:2 blgp:2
	v_mfma_scale_f32_16x16x128_f8f6f4 v[54:57], v[156:161], v[66:71], v[54:57], v200, v186 op_sel_hi:[0,0,0] cbsz:2 blgp:2
	v_mfma_scale_f32_16x16x128_f8f6f4 v[50:53], v[162:167], v[66:71], v[50:53], v204, v186 op_sel_hi:[0,0,0] cbsz:2 blgp:2
	v_mfma_scale_f32_16x16x128_f8f6f4 v[38:41], v[156:161], v[72:77], v[38:41], v200, v190 op_sel_hi:[0,0,0] cbsz:2 blgp:2
	v_mfma_scale_f32_16x16x128_f8f6f4 v[184:187], v[162:167], v[72:77], v[34:37], v204, v190 op_sel_hi:[0,0,0] cbsz:2 blgp:2
	v_mfma_scale_f32_16x16x128_f8f6f4 v[188:191], v[156:161], v[78:83], v[22:25], v200, v208 op_sel_hi:[0,0,0] cbsz:2 blgp:2
	v_mfma_scale_f32_16x16x128_f8f6f4 v[206:209], v[162:167], v[78:83], v[18:21], v204, v208 op_sel_hi:[0,0,0] cbsz:2 blgp:2
	v_mfma_scale_f32_16x16x128_f8f6f4 v[200:203], v[156:161], v[84:89], v[6:9], v200, v212 op_sel_hi:[0,0,0] cbsz:2 blgp:2
	v_mfma_scale_f32_16x16x128_f8f6f4 v[210:213], v[162:167], v[84:89], v[2:5], v204, v212 op_sel_hi:[0,0,0] cbsz:2 blgp:2
	s_barrier
	s_mov_b32 m0, s41
	ds_read_b128 v[2:5], v143
	ds_read_b128 v[230:233], v143 offset:1024
	ds_read_b128 v[8:11], v143 offset:2048
	ds_read_b128 v[234:237], v143 offset:3072
	ds_read_b128 v[144:147], v134
	ds_read_b128 v[238:241], v134 offset:1024
	ds_read_b128 v[150:153], v134 offset:2048
	ds_read_b128 v[242:245], v134 offset:3072
	ds_read_b128 v[14:17], v142 offset:32768
	ds_read_b128 v[66:69], v142 offset:33792
	ds_read_b128 v[20:23], v142 offset:34816
	ds_read_b128 v[70:73], v142 offset:35840
	ds_read_b128 v[26:29], v142 offset:36864
	ds_read_b128 v[80:83], v142 offset:37888
	global_load_lds_dwordx4 v[248:249], off
	s_mov_b32 m0, s42
	ds_read_b128 v[32:35], v142 offset:38912
	ds_read_b128 v[154:157], v142 offset:39936
	global_load_lds_dwordx4 v[250:251], off
	s_waitcnt vmcnt(8)
	s_waitcnt lgkmcnt(0)
	s_barrier
	s_waitcnt lgkmcnt(0)
	v_mov_b32_e32 v6, v230
	v_mov_b32_e32 v7, v231
	v_mov_b32_e32 v12, v234
	v_mov_b32_e32 v13, v235
	v_mov_b32_e32 v18, v66
	v_mov_b32_e32 v19, v67
	v_mov_b32_e32 v24, v70
	v_mov_b32_e32 v25, v71
	v_mov_b32_e32 v30, v80
	v_mov_b32_e32 v31, v81
	v_mov_b32_e32 v36, v154
	v_mov_b32_e32 v37, v155
	v_mfma_scale_f32_16x16x128_f8f6f4 v[126:129], v[2:7], v[14:19], v[126:129], v232, v68 op_sel_hi:[0,0,0] cbsz:2 blgp:2
	v_mfma_scale_f32_16x16x128_f8f6f4 v[122:125], v[8:13], v[14:19], v[122:125], v236, v68 op_sel_hi:[0,0,0] cbsz:2 blgp:2
	v_mfma_scale_f32_16x16x128_f8f6f4 v[110:113], v[2:7], v[20:25], v[110:113], v232, v72 op_sel_hi:[0,0,0] cbsz:2 blgp:2
	v_mfma_scale_f32_16x16x128_f8f6f4 v[106:109], v[8:13], v[20:25], v[106:109], v236, v72 op_sel_hi:[0,0,0] cbsz:2 blgp:2
	s_add_i32 s100, s46, s29
	s_add_i32 s101, s47, s29
	s_add_i32 s46, s47, s29
	v_lshl_add_u64 v[248:249], v[138:139], 0, s[24:25]
	v_lshl_add_u64 v[250:251], v[138:139], 0, s[26:27]
	v_lshl_add_u64 v[252:253], v[138:139], 0, s[30:31]
	v_mfma_scale_f32_16x16x128_f8f6f4 v[94:97], v[2:7], v[26:31], v[94:97], v232, v82 op_sel_hi:[0,0,0] cbsz:2 blgp:2
	v_mfma_scale_f32_16x16x128_f8f6f4 v[90:93], v[8:13], v[26:31], v[90:93], v236, v82 op_sel_hi:[0,0,0] cbsz:2 blgp:2
	v_mfma_scale_f32_16x16x128_f8f6f4 v[78:81], v[2:7], v[32:37], v[222:225], v232, v156 op_sel_hi:[0,0,0] cbsz:2 blgp:2
	v_mfma_scale_f32_16x16x128_f8f6f4 v[74:77], v[8:13], v[32:37], v[226:229], v236, v156 op_sel_hi:[0,0,0] cbsz:2 blgp:2
	v_mov_b32_e32 v148, v238
	v_mov_b32_e32 v149, v239
	v_mov_b32_e32 v154, v242
	v_mov_b32_e32 v155, v243
	v_mfma_scale_f32_16x16x128_f8f6f4 v[118:121], v[144:149], v[14:19], v[118:121], v240, v68 op_sel_hi:[0,0,0] cbsz:2 blgp:2
	s_nop 0
	v_mfma_scale_f32_16x16x128_f8f6f4 v[114:117], v[150:155], v[14:19], v[114:117], v244, v68 op_sel_hi:[0,0,0] cbsz:2 blgp:2
	v_mfma_scale_f32_16x16x128_f8f6f4 v[102:105], v[144:149], v[20:25], v[102:105], v240, v72 op_sel_hi:[0,0,0] cbsz:2 blgp:2
	v_mfma_scale_f32_16x16x128_f8f6f4 v[98:101], v[150:155], v[20:25], v[98:101], v244, v72 op_sel_hi:[0,0,0] cbsz:2 blgp:2
	v_mfma_scale_f32_16x16x128_f8f6f4 v[86:89], v[144:149], v[26:31], v[168:171], v240, v82 op_sel_hi:[0,0,0] cbsz:2 blgp:2
	v_mfma_scale_f32_16x16x128_f8f6f4 v[82:85], v[150:155], v[26:31], v[172:175], v244, v82 op_sel_hi:[0,0,0] cbsz:2 blgp:2
	v_mfma_scale_f32_16x16x128_f8f6f4 v[70:73], v[144:149], v[32:37], v[176:179], v240, v156 op_sel_hi:[0,0,0] cbsz:2 blgp:2
	v_mfma_scale_f32_16x16x128_f8f6f4 v[66:69], v[150:155], v[32:37], v[180:183], v244, v156 op_sel_hi:[0,0,0] cbsz:2 blgp:2
	s_barrier
	s_mov_b32 m0, s100
	ds_read_b128 v[18:21], v142 offset:49152
	ds_read_b128 v[22:25], v142 offset:50176
	ds_read_b128 v[156:159], v142 offset:51200
	global_load_lds_dwordx4 v[248:249], off
	s_add_i32 m0, s100, 0x2000
	ds_read_b128 v[32:35], v142 offset:52224
	global_load_lds_dwordx4 v[250:251], off
	s_mov_b32 m0, s101
	ds_read_b128 v[162:165], v142 offset:53248
	global_load_lds_dwordx4 v[252:253], off
	s_add_i32 m0, s101, 0x2000
	v_lshl_add_u64 v[14:15], v[138:139], 0, s[34:35]
	ds_read_b128 v[172:175], v142 offset:54272
	global_load_lds_dwordx4 v[14:15], off
	s_mov_b32 m0, s51
	v_lshl_add_u64 v[14:15], v[246:247], 0, s[24:25]
	ds_read_b128 v[168:171], v142 offset:55296
	global_load_lds_dwordx4 v[14:15], off
	s_mov_b32 m0, s52
	v_lshl_add_u64 v[14:15], v[246:247], 0, s[26:27]
	ds_read_b128 v[176:179], v142 offset:56320
	global_load_lds_dwordx4 v[14:15], off
	s_waitcnt vmcnt(8)
	s_waitcnt lgkmcnt(0)
	s_barrier
	s_waitcnt lgkmcnt(0)
	v_mov_b32_e32 v160, v32
	v_mov_b32_e32 v161, v33
	v_mov_b32_e32 v166, v172
	v_mov_b32_e32 v167, v173
	v_mov_b32_e32 v172, v176
	v_mov_b32_e32 v173, v177
	v_mfma_scale_f32_16x16x128_f8f6f4 v[62:65], v[2:7], v[18:23], v[62:65], v232, v24 op_sel_hi:[0,0,0] cbsz:2 blgp:2
	v_mfma_scale_f32_16x16x128_f8f6f4 v[58:61], v[8:13], v[18:23], v[58:61], v236, v24 op_sel_hi:[0,0,0] cbsz:2 blgp:2
	v_mfma_scale_f32_16x16x128_f8f6f4 v[46:49], v[2:7], v[156:161], v[46:49], v232, v34 op_sel_hi:[0,0,0] cbsz:2 blgp:2
	v_mfma_scale_f32_16x16x128_f8f6f4 v[42:45], v[8:13], v[156:161], v[42:45], v236, v34 op_sel_hi:[0,0,0] cbsz:2 blgp:2
	v_mfma_scale_f32_16x16x128_f8f6f4 v[30:33], v[2:7], v[162:167], v[214:217], v232, v174 op_sel_hi:[0,0,0] cbsz:2 blgp:2
	v_mfma_scale_f32_16x16x128_f8f6f4 v[26:29], v[8:13], v[162:167], v[218:221], v236, v174 op_sel_hi:[0,0,0] cbsz:2 blgp:2
	v_mfma_scale_f32_16x16x128_f8f6f4 v[14:17], v[2:7], v[168:173], v[192:195], v232, v178 op_sel_hi:[0,0,0] cbsz:2 blgp:2
	v_mfma_scale_f32_16x16x128_f8f6f4 v[10:13], v[8:13], v[168:173], v[196:199], v236, v178 op_sel_hi:[0,0,0] cbsz:2 blgp:2
	v_mfma_scale_f32_16x16x128_f8f6f4 v[54:57], v[144:149], v[18:23], v[54:57], v240, v24 op_sel_hi:[0,0,0] cbsz:2 blgp:2
	v_mfma_scale_f32_16x16x128_f8f6f4 v[50:53], v[150:155], v[18:23], v[50:53], v244, v24 op_sel_hi:[0,0,0] cbsz:2 blgp:2
	v_mfma_scale_f32_16x16x128_f8f6f4 v[38:41], v[144:149], v[156:161], v[38:41], v240, v34 op_sel_hi:[0,0,0] cbsz:2 blgp:2
	v_mfma_scale_f32_16x16x128_f8f6f4 v[34:37], v[150:155], v[156:161], v[184:187], v244, v34 op_sel_hi:[0,0,0] cbsz:2 blgp:2
	v_mfma_scale_f32_16x16x128_f8f6f4 v[22:25], v[144:149], v[162:167], v[188:191], v240, v174 op_sel_hi:[0,0,0] cbsz:2 blgp:2
	v_mfma_scale_f32_16x16x128_f8f6f4 v[18:21], v[150:155], v[162:167], v[206:209], v244, v174 op_sel_hi:[0,0,0] cbsz:2 blgp:2
	v_mfma_scale_f32_16x16x128_f8f6f4 v[6:9], v[144:149], v[168:173], v[200:203], v240, v178 op_sel_hi:[0,0,0] cbsz:2 blgp:2
	v_mfma_scale_f32_16x16x128_f8f6f4 v[2:5], v[150:155], v[168:173], v[210:213], v244, v178 op_sel_hi:[0,0,0] cbsz:2 blgp:2
	s_barrier
	s_add_u32 s44, s44, 0x100
	s_addc_u32 s45, s45, 0
	s_add_u32 s5, s5, 0x100
	s_addc_u32 s67, s67, 0
	s_cmp_ge_i32 s76, s66
	s_mov_b32 s46, s76
	s_cbranch_scc0 .LBB0_2291
	s_setprio 0
	v_readlane_b32 s76, v254, 6
	v_readlane_b32 s77, v254, 7
	v_readlane_b32 s78, v254, 8
	v_readlane_b32 s79, v254, 9
	v_readlane_b32 s80, v254, 10
	v_readlane_b32 s81, v254, 11
	v_readlane_b32 s82, v254, 12
	v_readlane_b32 s83, v254, 13
	s_and_b64 vcc, exec, s[36:37]
	s_cbranch_vccz .LBB0_2294
